# v019 + residual-epilogue loads batched (counted waits), scan carry-in loads batched, scalar adds in attention exp/PV block
# speedup vs baseline: 1.0152x; 1.0032x over previous
; __device__ __forceinline__ unsigned pk2(float lo, float hi) { f32x2v v = {lo, hi}; bf16x2v b = __builtin_convertvector(v, bf16x2v); return __builtin_bit_cast(unsigned, b); }
; DI f32x16 mfma32(bf16x8 a, bf16x8 b, f32x16 c) { return __builtin_amdgcn_mfma_f32_32x32x16_bf16(a, b, c, 0, 0, 0); }
; template <int VAR> DI void phase_attn(LAS unsigned char* lds, const bf16_t* Q, const bf16_t* K, const bf16_t* VT, bf16_t* O) {
;     ...
;                 float ls = 0.f;
; #pragma unroll
;                 for (int r = 0; r < 16; ++r) { if (VAR != 1) { p0[r] = __builtin_amdgcn_exp2f(p0[r]); p1[r] = __builtin_amdgcn_exp2f(p1[r]); } }
; #pragma unroll
;                 for (int r = 0; r < 16; r += 2) ls += (p0[r] + p0[r + 1]) + (p1[r] + p1[r + 1]);
;                 lrun += ls;
;                 bf16x8 pf[4];
;                 { u32x4 w;
;                   w.x = pk2(p0[0], p0[1]); w.y = pk2(p0[2], p0[3]); w.z = pk2(p0[4], p0[5]); w.w = pk2(p0[6], p0[7]); pf[0] = __builtin_bit_cast(bf16x8, w);
;                   w.x = pk2(p0[8], p0[9]); w.y = pk2(p0[10], p0[11]); w.z = pk2(p0[12], p0[13]); w.w = pk2(p0[14], p0[15]); pf[1] = __builtin_bit_cast(bf16x8, w);
;                   w.x = pk2(p1[0], p1[1]); w.y = pk2(p1[2], p1[3]); w.z = pk2(p1[4], p1[5]); w.w = pk2(p1[6], p1[7]); pf[2] = __builtin_bit_cast(bf16x8, w);
;                   w.x = pk2(p1[8], p1[9]); w.y = pk2(p1[10], p1[11]); w.z = pk2(p1[12], p1[13]); w.w = pk2(p1[14], p1[15]); pf[3] = __builtin_bit_cast(bf16x8, w); }
; #pragma unroll
;                 for (int f = 0; f < 4; ++f) { if (VAR == 2) { o0[f] += __builtin_bit_cast(f32x4, va[2 * f])[0] * __builtin_bit_cast(f32x4, pf[f])[1]; o1[f] += __builtin_bit_cast(f32x4, va[2 * f + 1])[2]; } else { o0 = mfma32(va[2 * f], pf[f], o0); o1 = mfma32(va[2 * f + 1], pf[f], o1); } }
.LBB0_74:
	v_exp_f32_e32 v173, v48
	v_exp_f32_e32 v49, v49
	v_exp_f32_e32 v172, v50
	v_exp_f32_e32 v48, v51
	v_exp_f32_e32 v50, v52
	v_exp_f32_e32 v51, v36
	v_exp_f32_e32 v36, v53
	v_exp_f32_e32 v53, v54
	v_exp_f32_e32 v210, v55
	v_exp_f32_e32 v175, v32
	v_exp_f32_e32 v209, v33
	v_exp_f32_e32 v174, v34
	v_exp_f32_e32 v208, v35
	v_cvt_pk_bf16_f32 v32, v173, v49
	v_cvt_pk_bf16_f32 v33, v172, v48
	v_cvt_pk_bf16_f32 v34, v50, v36
	v_cvt_pk_bf16_f32 v35, v53, v210
	v_exp_f32_e32 v206, v38
	v_exp_f32_e32 v38, v56
	s_waitcnt lgkmcnt(7)
	v_mfma_f32_32x32x16_bf16 v[0:15], v[130:133], v[32:35], v[0:15]
	v_exp_f32_e32 v52, v57
	v_exp_f32_e32 v56, v58
	v_exp_f32_e32 v57, v42
	v_exp_f32_e32 v42, v59
	v_exp_f32_e32 v59, v60
	v_exp_f32_e32 v130, v44
	v_exp_f32_e32 v61, v61
	s_waitcnt lgkmcnt(5)
	v_mfma_f32_32x32x16_bf16 v[16:31], v[126:129], v[32:35], v[16:31]
	v_exp_f32_e32 v44, v62
	v_exp_f32_e32 v58, v63
	v_cvt_pk_bf16_f32 v32, v38, v52
	v_cvt_pk_bf16_f32 v33, v56, v42
	v_cvt_pk_bf16_f32 v34, v59, v61
	v_cvt_pk_bf16_f32 v35, v44, v58
	v_exp_f32_e32 v37, v37
	v_exp_f32_e32 v211, v39
	v_mfma_f32_32x32x16_bf16 v[0:15], v[122:125], v[32:35], v[0:15]
	v_add_f32_e64 v48, v172, v48
	v_add_f32_e64 v49, v173, v49
	v_add_f32_e64 v62, v174, v208
	v_add_f32_e64 v63, v175, v209
	v_exp_f32_e32 v40, v40
	v_add_f32_e32 v48, v48, v62
	v_add_f32_e32 v49, v49, v63
	v_exp_f32_e32 v54, v41
	v_add_f32_e32 v39, 0, v49
	v_add_f32_e32 v55, v48, v39
	s_waitcnt lgkmcnt(4)
	v_mfma_f32_32x32x16_bf16 v[16:31], v[118:121], v[32:35], v[16:31]
	v_add_f32_e64 v32, v50, v36
	v_add_f32_e64 v33, v51, v37
	v_cvt_pk_bf16_f32 v34, v51, v37
	v_add_f32_e64 v48, v32, v32
	v_add_f32_e64 v49, v32, v33
	v_cvt_pk_bf16_f32 v32, v175, v209
	v_cvt_pk_bf16_f32 v33, v174, v208
	v_cvt_pk_bf16_f32 v35, v206, v211
	v_exp_f32_e32 v43, v43
	v_exp_f32_e32 v122, v45
	s_waitcnt lgkmcnt(3)
	v_mfma_f32_32x32x16_bf16 v[0:15], v[114:117], v[32:35], v[0:15]
	v_exp_f32_e32 v46, v46
	v_exp_f32_e32 v60, v47
	v_add_f32_e32 v39, v53, v210
	v_add_f32_e32 v53, v206, v211
	v_mov_b32_e32 v41, v49
	v_add_f32_e32 v36, v38, v52
	v_add_f32_e32 v37, v39, v53
	v_add_f32_e32 v38, v40, v54
	v_add_f32_e32 v39, v41, v55
	s_waitcnt lgkmcnt(1)
	v_mfma_f32_32x32x16_bf16 v[16:31], v[110:113], v[32:35], v[16:31]
	v_add_f32_e64 v32, v56, v42
	v_add_f32_e64 v33, v57, v43
	v_add_f32_e64 v36, v36, v38
	v_add_f32_e64 v37, v37, v39
	v_add_f32_e64 v38, v32, v32
	v_add_f32_e64 v39, v32, v33
	v_cvt_pk_bf16_f32 v32, v40, v54
	v_cvt_pk_bf16_f32 v33, v57, v43
	v_cvt_pk_bf16_f32 v34, v130, v122
	v_cvt_pk_bf16_f32 v35, v46, v60
	v_add_f32_e32 v37, v36, v37
	v_add_f32_e32 v36, v36, v36
	v_add_f32_e32 v45, v59, v61
	v_mfma_f32_32x32x16_bf16 v[0:15], v[106:109], v[32:35], v[0:15]
	v_add_f32_e32 v59, v130, v122
	v_mov_b32_e32 v47, v39
	v_mov_b32_e32 v61, v37
	v_add_f32_e64 v40, v44, v58
	v_add_f32_e64 v41, v45, v59
	v_add_f32_e32 v36, v46, v60
	v_add_f32_e32 v37, v47, v61
	s_nop 0
	v_add_f32_e32 v36, v40, v36
	v_add_f32_e32 v37, v41, v37
	s_waitcnt lgkmcnt(0)
	v_mfma_f32_32x32x16_bf16 v[16:31], v[102:105], v[32:35], v[16:31]
	v_add_f32_e32 v36, v36, v37
	v_add_f32_e32 v203, v203, v36
	s_andn2_b64 vcc, exec, s[0:1]
	s_cbranch_vccnz .LBB0_63

; DI void phase_scan2(const bf16_t* A, const bf16_t* U, const float* agg, const bf16_t* GATE, bf16_t* Y) {
;     ...
;         for (int cc = 0; cc < c; ++cc) { const float Pp = agg[((size_t)(b * 16 + cc) * 512 + ch) * 2], S = agg[((size_t)(b * 16 + cc) * 512 + ch) * 2 + 1]; h = Pp * h + S; }
.LBB0_121:
	v_add_co_u32_e32 v8, vcc, -4, v6
	s_mov_b64 s[6:7], 0x1000
	s_nop 0
	v_addc_co_u32_e32 v9, vcc, -1, v7, vcc
	global_load_dwordx2 v[100:101], v[8:9], off
	v_lshl_add_u64 v[8:9], v[8:9], 0, s[6:7]
	s_cmp_le_u32 s5, 1
	s_cbranch_scc1 .Lscan_ci_issued
	global_load_dwordx2 v[102:103], v[8:9], off
	v_lshl_add_u64 v[8:9], v[8:9], 0, s[6:7]
	s_cmp_le_u32 s5, 2
	s_cbranch_scc1 .Lscan_ci_issued
	global_load_dwordx2 v[104:105], v[8:9], off
	v_lshl_add_u64 v[8:9], v[8:9], 0, s[6:7]
	s_cmp_le_u32 s5, 3
	s_cbranch_scc1 .Lscan_ci_issued
	global_load_dwordx2 v[106:107], v[8:9], off
	v_lshl_add_u64 v[8:9], v[8:9], 0, s[6:7]
	s_cmp_le_u32 s5, 4
	s_cbranch_scc1 .Lscan_ci_issued
	global_load_dwordx2 v[108:109], v[8:9], off
	v_lshl_add_u64 v[8:9], v[8:9], 0, s[6:7]
	s_cmp_le_u32 s5, 5
	s_cbranch_scc1 .Lscan_ci_issued
	global_load_dwordx2 v[110:111], v[8:9], off
	v_lshl_add_u64 v[8:9], v[8:9], 0, s[6:7]
	s_cmp_le_u32 s5, 6
	s_cbranch_scc1 .Lscan_ci_issued
	global_load_dwordx2 v[112:113], v[8:9], off
	v_lshl_add_u64 v[8:9], v[8:9], 0, s[6:7]
	s_cmp_le_u32 s5, 7
	s_cbranch_scc1 .Lscan_ci_issued
	global_load_dwordx2 v[114:115], v[8:9], off
	v_lshl_add_u64 v[8:9], v[8:9], 0, s[6:7]
	s_cmp_le_u32 s5, 8
	s_cbranch_scc1 .Lscan_ci_issued
	global_load_dwordx2 v[116:117], v[8:9], off
	v_lshl_add_u64 v[8:9], v[8:9], 0, s[6:7]
	s_cmp_le_u32 s5, 9
	s_cbranch_scc1 .Lscan_ci_issued
	global_load_dwordx2 v[118:119], v[8:9], off
	v_lshl_add_u64 v[8:9], v[8:9], 0, s[6:7]
	s_cmp_le_u32 s5, 10
	s_cbranch_scc1 .Lscan_ci_issued
	global_load_dwordx2 v[120:121], v[8:9], off
	v_lshl_add_u64 v[8:9], v[8:9], 0, s[6:7]
	s_cmp_le_u32 s5, 11
	s_cbranch_scc1 .Lscan_ci_issued
	global_load_dwordx2 v[122:123], v[8:9], off
	v_lshl_add_u64 v[8:9], v[8:9], 0, s[6:7]
	s_cmp_le_u32 s5, 12
	s_cbranch_scc1 .Lscan_ci_issued
	global_load_dwordx2 v[124:125], v[8:9], off
	v_lshl_add_u64 v[8:9], v[8:9], 0, s[6:7]
	s_cmp_le_u32 s5, 13
	s_cbranch_scc1 .Lscan_ci_issued
	global_load_dwordx2 v[126:127], v[8:9], off
	v_lshl_add_u64 v[8:9], v[8:9], 0, s[6:7]
	s_cmp_le_u32 s5, 14
	s_cbranch_scc1 .Lscan_ci_issued
	global_load_dwordx2 v[128:129], v[8:9], off
	v_lshl_add_u64 v[8:9], v[8:9], 0, s[6:7]
.Lscan_ci_issued:
	s_waitcnt vmcnt(0)
	v_mov_b32_e32 v10, v20
	v_mov_b32_e32 v20, v101
	v_fmac_f32_e32 v20, v10, v100
	s_cmp_le_u32 s5, 1
	s_cbranch_scc1 .LBB0_123
	v_mov_b32_e32 v10, v20
	v_mov_b32_e32 v20, v103
	v_fmac_f32_e32 v20, v10, v102
	s_cmp_le_u32 s5, 2
	s_cbranch_scc1 .LBB0_123
	v_mov_b32_e32 v10, v20
	v_mov_b32_e32 v20, v105
	v_fmac_f32_e32 v20, v10, v104
	s_cmp_le_u32 s5, 3
	s_cbranch_scc1 .LBB0_123
	v_mov_b32_e32 v10, v20
	v_mov_b32_e32 v20, v107
	v_fmac_f32_e32 v20, v10, v106
	s_cmp_le_u32 s5, 4
	s_cbranch_scc1 .LBB0_123
	v_mov_b32_e32 v10, v20
	v_mov_b32_e32 v20, v109
	v_fmac_f32_e32 v20, v10, v108
	s_cmp_le_u32 s5, 5
	s_cbranch_scc1 .LBB0_123
	v_mov_b32_e32 v10, v20
	v_mov_b32_e32 v20, v111
	v_fmac_f32_e32 v20, v10, v110
	s_cmp_le_u32 s5, 6
	s_cbranch_scc1 .LBB0_123
	v_mov_b32_e32 v10, v20
	v_mov_b32_e32 v20, v113
	v_fmac_f32_e32 v20, v10, v112
	s_cmp_le_u32 s5, 7
	s_cbranch_scc1 .LBB0_123
	v_mov_b32_e32 v10, v20
	v_mov_b32_e32 v20, v115
	v_fmac_f32_e32 v20, v10, v114
	s_cmp_le_u32 s5, 8
	s_cbranch_scc1 .LBB0_123
	v_mov_b32_e32 v10, v20
	v_mov_b32_e32 v20, v117
	v_fmac_f32_e32 v20, v10, v116
	s_cmp_le_u32 s5, 9
	s_cbranch_scc1 .LBB0_123
	v_mov_b32_e32 v10, v20
	v_mov_b32_e32 v20, v119
	v_fmac_f32_e32 v20, v10, v118
	s_cmp_le_u32 s5, 10
	s_cbranch_scc1 .LBB0_123
	v_mov_b32_e32 v10, v20
	v_mov_b32_e32 v20, v121
	v_fmac_f32_e32 v20, v10, v120
	s_cmp_le_u32 s5, 11
	s_cbranch_scc1 .LBB0_123
	v_mov_b32_e32 v10, v20
	v_mov_b32_e32 v20, v123
	v_fmac_f32_e32 v20, v10, v122
	s_cmp_le_u32 s5, 12
	s_cbranch_scc1 .LBB0_123
	v_mov_b32_e32 v10, v20
	v_mov_b32_e32 v20, v125
	v_fmac_f32_e32 v20, v10, v124
	s_cmp_le_u32 s5, 13
	s_cbranch_scc1 .LBB0_123
	v_mov_b32_e32 v10, v20
	v_mov_b32_e32 v20, v127
	v_fmac_f32_e32 v20, v10, v126
	s_cmp_le_u32 s5, 14
	s_cbranch_scc1 .LBB0_123
	v_mov_b32_e32 v10, v20
	v_mov_b32_e32 v20, v129
	v_fmac_f32_e32 v20, v10, v128
	s_branch .LBB0_123

; #define GAS __attribute__((address_space(1)))
; __device__ __forceinline__ unsigned pk2(float lo, float hi) { f32x2v v = {lo, hi}; bf16x2v b = __builtin_convertvector(v, bf16x2v); return __builtin_bit_cast(unsigned, b); }
; #define GAS __attribute__((address_space(1)))
;     __device__ __forceinline__ void operator()(const f32x4 (&acc)[2][2][4][2], const Unit& u, int wr, int wc, int fr, int fq) const {
;     ...
;             for (int m = 0; m < 4; ++m) { const int row = row0 + ai * HALF + m * 16; bf16_t* bp = HB + (size_t)row * ld + c0; float sq = 0.f;
; #pragma unroll
;                 for (int bj = 0; bj < 2; ++bj) { GAS u32x4* p = (GAS u32x4*)(bp + bj * HALF); const u32x4 h = *p; const f32x4 a0 = acc[ai][bj][m][0], a1 = acc[ai][bj][m][1];
;                     const float v0 = __uint_as_float(h.x << 16) + a0[0], v1 = __uint_as_float(h.x & 0xffff0000u) + a0[1], v2 = __uint_as_float(h.y << 16) + a0[2], v3 = __uint_as_float(h.y & 0xffff0000u) + a0[3];
;                     const float v4 = __uint_as_float(h.z << 16) + a1[0], v5 = __uint_as_float(h.z & 0xffff0000u) + a1[1], v6 = __uint_as_float(h.w << 16) + a1[2], v7 = __uint_as_float(h.w & 0xffff0000u) + a1[3];
;                     u32x4 w; w.x = pk2(v0, v1); w.y = pk2(v2, v3); w.z = pk2(v4, v5); w.w = pk2(v6, v7); *p = w;
;                     sq += ((v0 * v0 + v1 * v1) + (v2 * v2 + v3 * v3)) + ((v4 * v4 + v5 * v5) + (v6 * v6 + v7 * v7)); }
;                 sq += __int_as_float(__builtin_amdgcn_ds_swizzle(__float_as_int(sq), (16 << 10) | 0x1f));
;                 { auto rr = __builtin_amdgcn_permlane32_swap(__float_as_uint(sq), __float_as_uint(sq), false, false); sq = __uint_as_float(rr[0]) + __uint_as_float(rr[1]); }
;                 if (fq == 0) ss[(size_t)row * 16 + u.pn * 4 + wc] = sq; }
.LBB0_478:
	s_andn2_b64 vcc, exec, s[6:7]
	s_cbranch_vccnz .LBB0_496
	s_waitcnt lgkmcnt(0)
	v_lshl_add_u32 v132, s64, 8, v208
	v_mad_u64_u32 v[134:135], vcc, v132, s15, 0
	v_ashrrev_i32_e32 v133, 31, v132
	v_mov_b32_e32 v64, v135
	v_mad_u64_u32 v[136:137], vcc, v133, s15, v[64:65]
	v_lshl_or_b32 v66, s11, 8, v210
	v_mov_b32_e32 v135, v136
	v_ashrrev_i32_e32 v67, 31, v66
	v_lshl_add_u64 v[134:135], v[134:135], 1, s[0:1]
	v_lshl_add_u64 v[142:143], v[66:67], 1, v[134:135]
	v_readlane_b32 s30, v255, 25
	v_readlane_b32 s31, v255, 26
	v_readlane_b32 s28, v255, 30
	s_lshl_b32 s16, s15, 5
	s_mov_b32 s17, 0
	s_mul_i32 s6, s15, 0xa0
	s_mov_b32 s7, 0
	v_lshl_add_u64 v[182:183], v[142:143], 0, 0
	global_load_dwordx4 v[184:187], v[142:143], off
	global_load_dwordx4 v[188:191], v[142:143], off offset:256
	v_lshl_add_u64 v[142:143], v[142:143], 0, s[16:17]
	global_load_dwordx4 v[192:195], v[142:143], off
	global_load_dwordx4 v[196:199], v[142:143], off offset:256
	v_lshl_add_u64 v[142:143], v[142:143], 0, s[16:17]
	global_load_dwordx4 v[200:203], v[142:143], off
	global_load_dwordx4 v[220:223], v[142:143], off offset:256
	v_lshl_add_u64 v[142:143], v[142:143], 0, s[16:17]
	global_load_dwordx4 v[224:227], v[142:143], off
	global_load_dwordx4 v[228:231], v[142:143], off offset:256
	v_lshl_add_u64 v[142:143], v[142:143], 0, s[6:7]
	global_load_dwordx4 v[232:235], v[142:143], off
	global_load_dwordx4 v[236:239], v[142:143], off offset:256
	v_lshl_add_u64 v[142:143], v[142:143], 0, s[16:17]
	global_load_dwordx4 v[240:243], v[142:143], off
	global_load_dwordx4 v[244:247], v[142:143], off offset:256
	v_lshl_add_u64 v[142:143], v[142:143], 0, s[16:17]
	global_load_dwordx4 v[134:137], v[142:143], off
	global_load_dwordx4 v[138:141], v[142:143], off offset:256
	v_lshl_add_u64 v[142:143], v[142:143], 0, s[16:17]
	global_load_dwordx4 v[144:147], v[142:143], off
	global_load_dwordx4 v[148:151], v[142:143], off offset:256
	s_lshl_b32 s98, s11, 2
	s_add_i32 s98, s98, s28
	s_lshl_b32 s98, s98, 2
	v_lshlrev_b64 v[66:67], 6, v[132:133]
	v_lshl_add_u64 v[66:67], s[50:51], 0, v[66:67]
	v_lshl_add_u64 v[66:67], v[66:67], 0, s[98:99]
	s_waitcnt vmcnt(15)
	v_lshlrev_b32_e32 v152, 16, v184
	v_and_b32_e32 v153, 0xffff0000, v184
	v_pk_add_f32 v[128:129], v[128:129], v[152:153]
	v_lshlrev_b32_e32 v154, 16, v185
	v_and_b32_e32 v155, 0xffff0000, v185
	v_pk_add_f32 v[130:131], v[130:131], v[154:155]
	v_lshlrev_b32_e32 v152, 16, v186
	v_and_b32_e32 v153, 0xffff0000, v186
	v_pk_add_f32 v[124:125], v[124:125], v[152:153]
	v_lshlrev_b32_e32 v154, 16, v187
	v_and_b32_e32 v155, 0xffff0000, v187
	v_pk_add_f32 v[126:127], v[126:127], v[154:155]
	v_cvt_pk_bf16_f32 v184, v128, v129
	v_cvt_pk_bf16_f32 v185, v130, v131
	v_cvt_pk_bf16_f32 v186, v124, v125
	v_cvt_pk_bf16_f32 v187, v126, v127
	global_store_dwordx4 v[182:183], v[184:187], off
	v_pk_mul_f32 v[128:129], v[128:129], v[128:129]
	v_pk_mul_f32 v[130:131], v[130:131], v[130:131]
	v_pk_mul_f32 v[124:125], v[124:125], v[124:125]
	v_pk_mul_f32 v[126:127], v[126:127], v[126:127]
	v_add_f32_e32 v126, v126, v127
	v_add_f32_e32 v124, v124, v125
	v_add_f32_e32 v130, v130, v131
	v_add_f32_e32 v128, v128, v129
	v_add_f32_e32 v124, v124, v126
	v_add_f32_e32 v128, v128, v130
	v_add_f32_e32 v128, v128, v124
	s_waitcnt vmcnt(15)
	v_lshlrev_b32_e32 v152, 16, v188
	v_and_b32_e32 v153, 0xffff0000, v188
	v_pk_add_f32 v[120:121], v[120:121], v[152:153]
	v_lshlrev_b32_e32 v154, 16, v189
	v_and_b32_e32 v155, 0xffff0000, v189
	v_pk_add_f32 v[122:123], v[122:123], v[154:155]
	v_lshlrev_b32_e32 v152, 16, v190
	v_and_b32_e32 v153, 0xffff0000, v190
	v_pk_add_f32 v[116:117], v[116:117], v[152:153]
	v_lshlrev_b32_e32 v154, 16, v191
	v_and_b32_e32 v155, 0xffff0000, v191
	v_pk_add_f32 v[118:119], v[118:119], v[154:155]
	v_cvt_pk_bf16_f32 v188, v120, v121
	v_cvt_pk_bf16_f32 v189, v122, v123
	v_cvt_pk_bf16_f32 v190, v116, v117
	v_cvt_pk_bf16_f32 v191, v118, v119
	global_store_dwordx4 v[182:183], v[188:191], off offset:256
	v_pk_mul_f32 v[120:121], v[120:121], v[120:121]
	v_pk_mul_f32 v[122:123], v[122:123], v[122:123]
	v_pk_mul_f32 v[116:117], v[116:117], v[116:117]
	v_pk_mul_f32 v[118:119], v[118:119], v[118:119]
	v_add_f32_e32 v118, v118, v119
	v_add_f32_e32 v116, v116, v117
	v_add_f32_e32 v122, v122, v123
	v_add_f32_e32 v120, v120, v121
	v_add_f32_e32 v116, v116, v118
	v_add_f32_e32 v120, v120, v122
	v_add_f32_e32 v120, v120, v116
	v_add_f32_e32 v128, v128, v120
	ds_swizzle_b32 v129, v128 offset:swizzle(SWAP,16)
	v_lshl_add_u64 v[182:183], v[182:183], 0, s[16:17]
	s_waitcnt vmcnt(15)
	v_lshlrev_b32_e32 v152, 16, v192
	v_and_b32_e32 v153, 0xffff0000, v192
	v_pk_add_f32 v[112:113], v[112:113], v[152:153]
	v_lshlrev_b32_e32 v154, 16, v193
	v_and_b32_e32 v155, 0xffff0000, v193
	v_pk_add_f32 v[114:115], v[114:115], v[154:155]
	v_lshlrev_b32_e32 v152, 16, v194
	v_and_b32_e32 v153, 0xffff0000, v194
	v_pk_add_f32 v[108:109], v[108:109], v[152:153]
	v_lshlrev_b32_e32 v154, 16, v195
	v_and_b32_e32 v155, 0xffff0000, v195
	v_pk_add_f32 v[110:111], v[110:111], v[154:155]
	v_cvt_pk_bf16_f32 v192, v112, v113
	v_cvt_pk_bf16_f32 v193, v114, v115
	v_cvt_pk_bf16_f32 v194, v108, v109
	v_cvt_pk_bf16_f32 v195, v110, v111
	global_store_dwordx4 v[182:183], v[192:195], off
	v_pk_mul_f32 v[112:113], v[112:113], v[112:113]
	v_pk_mul_f32 v[114:115], v[114:115], v[114:115]
	v_pk_mul_f32 v[108:109], v[108:109], v[108:109]
	v_pk_mul_f32 v[110:111], v[110:111], v[110:111]
	v_add_f32_e32 v110, v110, v111
	v_add_f32_e32 v108, v108, v109
	v_add_f32_e32 v114, v114, v115
	v_add_f32_e32 v112, v112, v113
	v_add_f32_e32 v108, v108, v110
	v_add_f32_e32 v112, v112, v114
	v_add_f32_e32 v112, v112, v108
	s_waitcnt vmcnt(15)
; #define GAS __attribute__((address_space(1)))
; __device__ __forceinline__ unsigned pk2(float lo, float hi) { f32x2v v = {lo, hi}; bf16x2v b = __builtin_convertvector(v, bf16x2v); return __builtin_bit_cast(unsigned, b); }
; #define GAS __attribute__((address_space(1)))
;     __device__ __forceinline__ void operator()(const f32x4 (&acc)[2][2][4][2], const Unit& u, int wr, int wc, int fr, int fq) const {
;     ...
;             for (int m = 0; m < 4; ++m) { const int row = row0 + ai * HALF + m * 16; bf16_t* bp = HB + (size_t)row * ld + c0; float sq = 0.f;
; #pragma unroll
;                 for (int bj = 0; bj < 2; ++bj) { GAS u32x4* p = (GAS u32x4*)(bp + bj * HALF); const u32x4 h = *p; const f32x4 a0 = acc[ai][bj][m][0], a1 = acc[ai][bj][m][1];
;                     const float v0 = __uint_as_float(h.x << 16) + a0[0], v1 = __uint_as_float(h.x & 0xffff0000u) + a0[1], v2 = __uint_as_float(h.y << 16) + a0[2], v3 = __uint_as_float(h.y & 0xffff0000u) + a0[3];
;                     const float v4 = __uint_as_float(h.z << 16) + a1[0], v5 = __uint_as_float(h.z & 0xffff0000u) + a1[1], v6 = __uint_as_float(h.w << 16) + a1[2], v7 = __uint_as_float(h.w & 0xffff0000u) + a1[3];
;                     u32x4 w; w.x = pk2(v0, v1); w.y = pk2(v2, v3); w.z = pk2(v4, v5); w.w = pk2(v6, v7); *p = w;
;                     sq += ((v0 * v0 + v1 * v1) + (v2 * v2 + v3 * v3)) + ((v4 * v4 + v5 * v5) + (v6 * v6 + v7 * v7)); }
;                 sq += __int_as_float(__builtin_amdgcn_ds_swizzle(__float_as_int(sq), (16 << 10) | 0x1f));
;                 { auto rr = __builtin_amdgcn_permlane32_swap(__float_as_uint(sq), __float_as_uint(sq), false, false); sq = __uint_as_float(rr[0]) + __uint_as_float(rr[1]); }
;                 if (fq == 0) ss[(size_t)row * 16 + u.pn * 4 + wc] = sq; }
	v_lshlrev_b32_e32 v152, 16, v196
	v_and_b32_e32 v153, 0xffff0000, v196
	v_pk_add_f32 v[104:105], v[104:105], v[152:153]
	v_lshlrev_b32_e32 v154, 16, v197
	v_and_b32_e32 v155, 0xffff0000, v197
	v_pk_add_f32 v[106:107], v[106:107], v[154:155]
	v_lshlrev_b32_e32 v152, 16, v198
	v_and_b32_e32 v153, 0xffff0000, v198
	v_pk_add_f32 v[100:101], v[100:101], v[152:153]
	v_lshlrev_b32_e32 v154, 16, v199
	v_and_b32_e32 v155, 0xffff0000, v199
	v_pk_add_f32 v[102:103], v[102:103], v[154:155]
	v_cvt_pk_bf16_f32 v196, v104, v105
	v_cvt_pk_bf16_f32 v197, v106, v107
	v_cvt_pk_bf16_f32 v198, v100, v101
	v_cvt_pk_bf16_f32 v199, v102, v103
	global_store_dwordx4 v[182:183], v[196:199], off offset:256
	v_pk_mul_f32 v[104:105], v[104:105], v[104:105]
	v_pk_mul_f32 v[106:107], v[106:107], v[106:107]
	v_pk_mul_f32 v[100:101], v[100:101], v[100:101]
	v_pk_mul_f32 v[102:103], v[102:103], v[102:103]
	v_add_f32_e32 v102, v102, v103
	v_add_f32_e32 v100, v100, v101
	v_add_f32_e32 v106, v106, v107
	v_add_f32_e32 v104, v104, v105
	v_add_f32_e32 v100, v100, v102
	v_add_f32_e32 v104, v104, v106
	v_add_f32_e32 v104, v104, v100
	v_add_f32_e32 v112, v112, v104
	ds_swizzle_b32 v113, v112 offset:swizzle(SWAP,16)
	v_lshl_add_u64 v[182:183], v[182:183], 0, s[16:17]
	s_waitcnt vmcnt(15)
	v_lshlrev_b32_e32 v152, 16, v200
	v_and_b32_e32 v153, 0xffff0000, v200
	v_pk_add_f32 v[96:97], v[96:97], v[152:153]
	v_lshlrev_b32_e32 v154, 16, v201
	v_and_b32_e32 v155, 0xffff0000, v201
	v_pk_add_f32 v[98:99], v[98:99], v[154:155]
	v_lshlrev_b32_e32 v152, 16, v202
	v_and_b32_e32 v153, 0xffff0000, v202
	v_pk_add_f32 v[92:93], v[92:93], v[152:153]
	v_lshlrev_b32_e32 v154, 16, v203
	v_and_b32_e32 v155, 0xffff0000, v203
	v_pk_add_f32 v[94:95], v[94:95], v[154:155]
	v_cvt_pk_bf16_f32 v200, v96, v97
	v_cvt_pk_bf16_f32 v201, v98, v99
	v_cvt_pk_bf16_f32 v202, v92, v93
	v_cvt_pk_bf16_f32 v203, v94, v95
	global_store_dwordx4 v[182:183], v[200:203], off
	v_pk_mul_f32 v[96:97], v[96:97], v[96:97]
	v_pk_mul_f32 v[98:99], v[98:99], v[98:99]
	v_pk_mul_f32 v[92:93], v[92:93], v[92:93]
	v_pk_mul_f32 v[94:95], v[94:95], v[94:95]
	v_add_f32_e32 v94, v94, v95
	v_add_f32_e32 v92, v92, v93
	v_add_f32_e32 v98, v98, v99
	v_add_f32_e32 v96, v96, v97
	v_add_f32_e32 v92, v92, v94
	v_add_f32_e32 v96, v96, v98
	v_add_f32_e32 v96, v96, v92
	s_waitcnt vmcnt(15)
	v_lshlrev_b32_e32 v152, 16, v220
	v_and_b32_e32 v153, 0xffff0000, v220
	v_pk_add_f32 v[88:89], v[88:89], v[152:153]
	v_lshlrev_b32_e32 v154, 16, v221
	v_and_b32_e32 v155, 0xffff0000, v221
	v_pk_add_f32 v[90:91], v[90:91], v[154:155]
	v_lshlrev_b32_e32 v152, 16, v222
	v_and_b32_e32 v153, 0xffff0000, v222
	v_pk_add_f32 v[84:85], v[84:85], v[152:153]
	v_lshlrev_b32_e32 v154, 16, v223
	v_and_b32_e32 v155, 0xffff0000, v223
	v_pk_add_f32 v[86:87], v[86:87], v[154:155]
	v_cvt_pk_bf16_f32 v220, v88, v89
	v_cvt_pk_bf16_f32 v221, v90, v91
	v_cvt_pk_bf16_f32 v222, v84, v85
	v_cvt_pk_bf16_f32 v223, v86, v87
	global_store_dwordx4 v[182:183], v[220:223], off offset:256
	v_pk_mul_f32 v[88:89], v[88:89], v[88:89]
	v_pk_mul_f32 v[90:91], v[90:91], v[90:91]
	v_pk_mul_f32 v[84:85], v[84:85], v[84:85]
	v_pk_mul_f32 v[86:87], v[86:87], v[86:87]
	v_add_f32_e32 v86, v86, v87
	v_add_f32_e32 v84, v84, v85
	v_add_f32_e32 v90, v90, v91
	v_add_f32_e32 v88, v88, v89
	v_add_f32_e32 v84, v84, v86
	v_add_f32_e32 v88, v88, v90
	v_add_f32_e32 v88, v88, v84
	v_add_f32_e32 v96, v96, v88
	ds_swizzle_b32 v97, v96 offset:swizzle(SWAP,16)
	v_lshl_add_u64 v[182:183], v[182:183], 0, s[16:17]
	s_waitcnt vmcnt(15)
	v_lshlrev_b32_e32 v152, 16, v224
	v_and_b32_e32 v153, 0xffff0000, v224
	v_pk_add_f32 v[80:81], v[80:81], v[152:153]
	v_lshlrev_b32_e32 v154, 16, v225
	v_and_b32_e32 v155, 0xffff0000, v225
	v_pk_add_f32 v[82:83], v[82:83], v[154:155]
	v_lshlrev_b32_e32 v152, 16, v226
	v_and_b32_e32 v153, 0xffff0000, v226
	v_pk_add_f32 v[76:77], v[76:77], v[152:153]
	v_lshlrev_b32_e32 v154, 16, v227
	v_and_b32_e32 v155, 0xffff0000, v227
	v_pk_add_f32 v[78:79], v[78:79], v[154:155]
	v_cvt_pk_bf16_f32 v224, v80, v81
	v_cvt_pk_bf16_f32 v225, v82, v83
	v_cvt_pk_bf16_f32 v226, v76, v77
	v_cvt_pk_bf16_f32 v227, v78, v79
	global_store_dwordx4 v[182:183], v[224:227], off
	v_pk_mul_f32 v[80:81], v[80:81], v[80:81]
	v_pk_mul_f32 v[82:83], v[82:83], v[82:83]
	v_pk_mul_f32 v[76:77], v[76:77], v[76:77]
	v_pk_mul_f32 v[78:79], v[78:79], v[78:79]
	v_add_f32_e32 v78, v78, v79
	v_add_f32_e32 v76, v76, v77
	v_add_f32_e32 v82, v82, v83
	v_add_f32_e32 v80, v80, v81
	v_add_f32_e32 v76, v76, v78
	v_add_f32_e32 v80, v80, v82
	v_add_f32_e32 v80, v80, v76
	s_waitcnt vmcnt(15)
	v_lshlrev_b32_e32 v152, 16, v228
	v_and_b32_e32 v153, 0xffff0000, v228
	v_pk_add_f32 v[72:73], v[72:73], v[152:153]
	v_lshlrev_b32_e32 v154, 16, v229
	v_and_b32_e32 v155, 0xffff0000, v229
	v_pk_add_f32 v[74:75], v[74:75], v[154:155]
	v_lshlrev_b32_e32 v152, 16, v230
	v_and_b32_e32 v153, 0xffff0000, v230
	v_pk_add_f32 v[68:69], v[68:69], v[152:153]
	v_lshlrev_b32_e32 v154, 16, v231
	v_and_b32_e32 v155, 0xffff0000, v231
	v_pk_add_f32 v[70:71], v[70:71], v[154:155]
	v_cvt_pk_bf16_f32 v228, v72, v73
	v_cvt_pk_bf16_f32 v229, v74, v75
	v_cvt_pk_bf16_f32 v230, v68, v69
	v_cvt_pk_bf16_f32 v231, v70, v71
	global_store_dwordx4 v[182:183], v[228:231], off offset:256
	v_pk_mul_f32 v[72:73], v[72:73], v[72:73]
	v_pk_mul_f32 v[74:75], v[74:75], v[74:75]
	v_pk_mul_f32 v[68:69], v[68:69], v[68:69]
	v_pk_mul_f32 v[70:71], v[70:71], v[70:71]
	v_add_f32_e32 v70, v70, v71
	v_add_f32_e32 v68, v68, v69
	v_add_f32_e32 v74, v74, v75
	v_add_f32_e32 v72, v72, v73
	v_add_f32_e32 v68, v68, v70
	v_add_f32_e32 v72, v72, v74
	v_add_f32_e32 v72, v72, v68
	v_add_f32_e32 v80, v80, v72
	ds_swizzle_b32 v81, v80 offset:swizzle(SWAP,16)
	v_lshl_add_u64 v[182:183], v[182:183], 0, s[6:7]
	s_waitcnt vmcnt(15)
; #define GAS __attribute__((address_space(1)))
; __device__ __forceinline__ unsigned pk2(float lo, float hi) { f32x2v v = {lo, hi}; bf16x2v b = __builtin_convertvector(v, bf16x2v); return __builtin_bit_cast(unsigned, b); }
; #define GAS __attribute__((address_space(1)))
;     __device__ __forceinline__ void operator()(const f32x4 (&acc)[2][2][4][2], const Unit& u, int wr, int wc, int fr, int fq) const {
;     ...
;             for (int m = 0; m < 4; ++m) { const int row = row0 + ai * HALF + m * 16; bf16_t* bp = HB + (size_t)row * ld + c0; float sq = 0.f;
; #pragma unroll
;                 for (int bj = 0; bj < 2; ++bj) { GAS u32x4* p = (GAS u32x4*)(bp + bj * HALF); const u32x4 h = *p; const f32x4 a0 = acc[ai][bj][m][0], a1 = acc[ai][bj][m][1];
;                     const float v0 = __uint_as_float(h.x << 16) + a0[0], v1 = __uint_as_float(h.x & 0xffff0000u) + a0[1], v2 = __uint_as_float(h.y << 16) + a0[2], v3 = __uint_as_float(h.y & 0xffff0000u) + a0[3];
;                     const float v4 = __uint_as_float(h.z << 16) + a1[0], v5 = __uint_as_float(h.z & 0xffff0000u) + a1[1], v6 = __uint_as_float(h.w << 16) + a1[2], v7 = __uint_as_float(h.w & 0xffff0000u) + a1[3];
;                     u32x4 w; w.x = pk2(v0, v1); w.y = pk2(v2, v3); w.z = pk2(v4, v5); w.w = pk2(v6, v7); *p = w;
;                     sq += ((v0 * v0 + v1 * v1) + (v2 * v2 + v3 * v3)) + ((v4 * v4 + v5 * v5) + (v6 * v6 + v7 * v7)); }
;                 sq += __int_as_float(__builtin_amdgcn_ds_swizzle(__float_as_int(sq), (16 << 10) | 0x1f));
;                 { auto rr = __builtin_amdgcn_permlane32_swap(__float_as_uint(sq), __float_as_uint(sq), false, false); sq = __uint_as_float(rr[0]) + __uint_as_float(rr[1]); }
;                 if (fq == 0) ss[(size_t)row * 16 + u.pn * 4 + wc] = sq; }
	v_lshlrev_b32_e32 v152, 16, v232
	v_and_b32_e32 v153, 0xffff0000, v232
	v_pk_add_f32 v[60:61], v[60:61], v[152:153]
	v_lshlrev_b32_e32 v154, 16, v233
	v_and_b32_e32 v155, 0xffff0000, v233
	v_pk_add_f32 v[62:63], v[62:63], v[154:155]
	v_lshlrev_b32_e32 v152, 16, v234
	v_and_b32_e32 v153, 0xffff0000, v234
	v_pk_add_f32 v[56:57], v[56:57], v[152:153]
	v_lshlrev_b32_e32 v154, 16, v235
	v_and_b32_e32 v155, 0xffff0000, v235
	v_pk_add_f32 v[58:59], v[58:59], v[154:155]
	v_cvt_pk_bf16_f32 v232, v60, v61
	v_cvt_pk_bf16_f32 v233, v62, v63
	v_cvt_pk_bf16_f32 v234, v56, v57
	v_cvt_pk_bf16_f32 v235, v58, v59
	global_store_dwordx4 v[182:183], v[232:235], off
	v_pk_mul_f32 v[60:61], v[60:61], v[60:61]
	v_pk_mul_f32 v[62:63], v[62:63], v[62:63]
	v_pk_mul_f32 v[56:57], v[56:57], v[56:57]
	v_pk_mul_f32 v[58:59], v[58:59], v[58:59]
	v_add_f32_e32 v58, v58, v59
	v_add_f32_e32 v56, v56, v57
	v_add_f32_e32 v62, v62, v63
	v_add_f32_e32 v60, v60, v61
	v_add_f32_e32 v56, v56, v58
	v_add_f32_e32 v60, v60, v62
	v_add_f32_e32 v60, v60, v56
	s_waitcnt vmcnt(15)
	v_lshlrev_b32_e32 v152, 16, v236
	v_and_b32_e32 v153, 0xffff0000, v236
	v_pk_add_f32 v[52:53], v[52:53], v[152:153]
	v_lshlrev_b32_e32 v154, 16, v237
	v_and_b32_e32 v155, 0xffff0000, v237
	v_pk_add_f32 v[54:55], v[54:55], v[154:155]
	v_lshlrev_b32_e32 v152, 16, v238
	v_and_b32_e32 v153, 0xffff0000, v238
	v_pk_add_f32 v[48:49], v[48:49], v[152:153]
	v_lshlrev_b32_e32 v154, 16, v239
	v_and_b32_e32 v155, 0xffff0000, v239
	v_pk_add_f32 v[50:51], v[50:51], v[154:155]
	v_cvt_pk_bf16_f32 v236, v52, v53
	v_cvt_pk_bf16_f32 v237, v54, v55
	v_cvt_pk_bf16_f32 v238, v48, v49
	v_cvt_pk_bf16_f32 v239, v50, v51
	global_store_dwordx4 v[182:183], v[236:239], off offset:256
	v_pk_mul_f32 v[52:53], v[52:53], v[52:53]
	v_pk_mul_f32 v[54:55], v[54:55], v[54:55]
	v_pk_mul_f32 v[48:49], v[48:49], v[48:49]
	v_pk_mul_f32 v[50:51], v[50:51], v[50:51]
	v_add_f32_e32 v50, v50, v51
	v_add_f32_e32 v48, v48, v49
	v_add_f32_e32 v54, v54, v55
	v_add_f32_e32 v52, v52, v53
	v_add_f32_e32 v48, v48, v50
	v_add_f32_e32 v52, v52, v54
	v_add_f32_e32 v52, v52, v48
	v_add_f32_e32 v60, v60, v52
	ds_swizzle_b32 v61, v60 offset:swizzle(SWAP,16)
	v_lshl_add_u64 v[182:183], v[182:183], 0, s[16:17]
	s_waitcnt vmcnt(15)
	v_lshlrev_b32_e32 v152, 16, v240
	v_and_b32_e32 v153, 0xffff0000, v240
	v_pk_add_f32 v[44:45], v[44:45], v[152:153]
	v_lshlrev_b32_e32 v154, 16, v241
	v_and_b32_e32 v155, 0xffff0000, v241
	v_pk_add_f32 v[46:47], v[46:47], v[154:155]
	v_lshlrev_b32_e32 v152, 16, v242
	v_and_b32_e32 v153, 0xffff0000, v242
	v_pk_add_f32 v[40:41], v[40:41], v[152:153]
	v_lshlrev_b32_e32 v154, 16, v243
	v_and_b32_e32 v155, 0xffff0000, v243
	v_pk_add_f32 v[42:43], v[42:43], v[154:155]
	v_cvt_pk_bf16_f32 v240, v44, v45
	v_cvt_pk_bf16_f32 v241, v46, v47
	v_cvt_pk_bf16_f32 v242, v40, v41
	v_cvt_pk_bf16_f32 v243, v42, v43
	global_store_dwordx4 v[182:183], v[240:243], off
	v_pk_mul_f32 v[44:45], v[44:45], v[44:45]
	v_pk_mul_f32 v[46:47], v[46:47], v[46:47]
	v_pk_mul_f32 v[40:41], v[40:41], v[40:41]
	v_pk_mul_f32 v[42:43], v[42:43], v[42:43]
	v_add_f32_e32 v42, v42, v43
	v_add_f32_e32 v40, v40, v41
	v_add_f32_e32 v46, v46, v47
	v_add_f32_e32 v44, v44, v45
	v_add_f32_e32 v40, v40, v42
	v_add_f32_e32 v44, v44, v46
	v_add_f32_e32 v44, v44, v40
	s_waitcnt vmcnt(15)
	v_lshlrev_b32_e32 v152, 16, v244
	v_and_b32_e32 v153, 0xffff0000, v244
	v_pk_add_f32 v[36:37], v[36:37], v[152:153]
	v_lshlrev_b32_e32 v154, 16, v245
	v_and_b32_e32 v155, 0xffff0000, v245
	v_pk_add_f32 v[38:39], v[38:39], v[154:155]
	v_lshlrev_b32_e32 v152, 16, v246
	v_and_b32_e32 v153, 0xffff0000, v246
	v_pk_add_f32 v[32:33], v[32:33], v[152:153]
	v_lshlrev_b32_e32 v154, 16, v247
	v_and_b32_e32 v155, 0xffff0000, v247
	v_pk_add_f32 v[34:35], v[34:35], v[154:155]
	v_cvt_pk_bf16_f32 v244, v36, v37
	v_cvt_pk_bf16_f32 v245, v38, v39
	v_cvt_pk_bf16_f32 v246, v32, v33
	v_cvt_pk_bf16_f32 v247, v34, v35
	global_store_dwordx4 v[182:183], v[244:247], off offset:256
	v_pk_mul_f32 v[36:37], v[36:37], v[36:37]
	v_pk_mul_f32 v[38:39], v[38:39], v[38:39]
	v_pk_mul_f32 v[32:33], v[32:33], v[32:33]
	v_pk_mul_f32 v[34:35], v[34:35], v[34:35]
	v_add_f32_e32 v34, v34, v35
	v_add_f32_e32 v32, v32, v33
	v_add_f32_e32 v38, v38, v39
	v_add_f32_e32 v36, v36, v37
	v_add_f32_e32 v32, v32, v34
	v_add_f32_e32 v36, v36, v38
	v_add_f32_e32 v36, v36, v32
	v_add_f32_e32 v44, v44, v36
	ds_swizzle_b32 v45, v44 offset:swizzle(SWAP,16)
	v_lshl_add_u64 v[182:183], v[182:183], 0, s[16:17]
	s_waitcnt vmcnt(15)
	v_lshlrev_b32_e32 v152, 16, v134
	v_and_b32_e32 v153, 0xffff0000, v134
	v_pk_add_f32 v[28:29], v[28:29], v[152:153]
	v_lshlrev_b32_e32 v154, 16, v135
	v_and_b32_e32 v155, 0xffff0000, v135
	v_pk_add_f32 v[30:31], v[30:31], v[154:155]
	v_lshlrev_b32_e32 v152, 16, v136
	v_and_b32_e32 v153, 0xffff0000, v136
	v_pk_add_f32 v[24:25], v[24:25], v[152:153]
	v_lshlrev_b32_e32 v154, 16, v137
	v_and_b32_e32 v155, 0xffff0000, v137
	v_pk_add_f32 v[26:27], v[26:27], v[154:155]
	v_cvt_pk_bf16_f32 v134, v28, v29
	v_cvt_pk_bf16_f32 v135, v30, v31
	v_cvt_pk_bf16_f32 v136, v24, v25
	v_cvt_pk_bf16_f32 v137, v26, v27
	global_store_dwordx4 v[182:183], v[134:137], off
	v_pk_mul_f32 v[28:29], v[28:29], v[28:29]
	v_pk_mul_f32 v[30:31], v[30:31], v[30:31]
	v_pk_mul_f32 v[24:25], v[24:25], v[24:25]
	v_pk_mul_f32 v[26:27], v[26:27], v[26:27]
	v_add_f32_e32 v26, v26, v27
	v_add_f32_e32 v24, v24, v25
	v_add_f32_e32 v30, v30, v31
	v_add_f32_e32 v28, v28, v29
	v_add_f32_e32 v24, v24, v26
	v_add_f32_e32 v28, v28, v30
	v_add_f32_e32 v28, v28, v24
	s_waitcnt vmcnt(15)
; #define GAS __attribute__((address_space(1)))
; __device__ __forceinline__ unsigned pk2(float lo, float hi) { f32x2v v = {lo, hi}; bf16x2v b = __builtin_convertvector(v, bf16x2v); return __builtin_bit_cast(unsigned, b); }
; #define GAS __attribute__((address_space(1)))
;     __device__ __forceinline__ void operator()(const f32x4 (&acc)[2][2][4][2], const Unit& u, int wr, int wc, int fr, int fq) const {
;     ...
;             for (int m = 0; m < 4; ++m) { const int row = row0 + ai * HALF + m * 16; bf16_t* bp = HB + (size_t)row * ld + c0; float sq = 0.f;
; #pragma unroll
;                 for (int bj = 0; bj < 2; ++bj) { GAS u32x4* p = (GAS u32x4*)(bp + bj * HALF); const u32x4 h = *p; const f32x4 a0 = acc[ai][bj][m][0], a1 = acc[ai][bj][m][1];
;                     const float v0 = __uint_as_float(h.x << 16) + a0[0], v1 = __uint_as_float(h.x & 0xffff0000u) + a0[1], v2 = __uint_as_float(h.y << 16) + a0[2], v3 = __uint_as_float(h.y & 0xffff0000u) + a0[3];
;                     const float v4 = __uint_as_float(h.z << 16) + a1[0], v5 = __uint_as_float(h.z & 0xffff0000u) + a1[1], v6 = __uint_as_float(h.w << 16) + a1[2], v7 = __uint_as_float(h.w & 0xffff0000u) + a1[3];
;                     u32x4 w; w.x = pk2(v0, v1); w.y = pk2(v2, v3); w.z = pk2(v4, v5); w.w = pk2(v6, v7); *p = w;
;                     sq += ((v0 * v0 + v1 * v1) + (v2 * v2 + v3 * v3)) + ((v4 * v4 + v5 * v5) + (v6 * v6 + v7 * v7)); }
;                 sq += __int_as_float(__builtin_amdgcn_ds_swizzle(__float_as_int(sq), (16 << 10) | 0x1f));
;                 { auto rr = __builtin_amdgcn_permlane32_swap(__float_as_uint(sq), __float_as_uint(sq), false, false); sq = __uint_as_float(rr[0]) + __uint_as_float(rr[1]); }
;                 if (fq == 0) ss[(size_t)row * 16 + u.pn * 4 + wc] = sq; }
	v_lshlrev_b32_e32 v152, 16, v138
	v_and_b32_e32 v153, 0xffff0000, v138
	v_pk_add_f32 v[20:21], v[20:21], v[152:153]
	v_lshlrev_b32_e32 v154, 16, v139
	v_and_b32_e32 v155, 0xffff0000, v139
	v_pk_add_f32 v[22:23], v[22:23], v[154:155]
	v_lshlrev_b32_e32 v152, 16, v140
	v_and_b32_e32 v153, 0xffff0000, v140
	v_pk_add_f32 v[16:17], v[16:17], v[152:153]
	v_lshlrev_b32_e32 v154, 16, v141
	v_and_b32_e32 v155, 0xffff0000, v141
	v_pk_add_f32 v[18:19], v[18:19], v[154:155]
	v_cvt_pk_bf16_f32 v138, v20, v21
	v_cvt_pk_bf16_f32 v139, v22, v23
	v_cvt_pk_bf16_f32 v140, v16, v17
	v_cvt_pk_bf16_f32 v141, v18, v19
	global_store_dwordx4 v[182:183], v[138:141], off offset:256
	v_pk_mul_f32 v[20:21], v[20:21], v[20:21]
	v_pk_mul_f32 v[22:23], v[22:23], v[22:23]
	v_pk_mul_f32 v[16:17], v[16:17], v[16:17]
	v_pk_mul_f32 v[18:19], v[18:19], v[18:19]
	v_add_f32_e32 v18, v18, v19
	v_add_f32_e32 v16, v16, v17
	v_add_f32_e32 v22, v22, v23
	v_add_f32_e32 v20, v20, v21
	v_add_f32_e32 v16, v16, v18
	v_add_f32_e32 v20, v20, v22
	v_add_f32_e32 v20, v20, v16
	v_add_f32_e32 v28, v28, v20
	ds_swizzle_b32 v29, v28 offset:swizzle(SWAP,16)
	v_lshl_add_u64 v[182:183], v[182:183], 0, s[16:17]
	s_waitcnt vmcnt(15)
	v_lshlrev_b32_e32 v152, 16, v144
	v_and_b32_e32 v153, 0xffff0000, v144
	v_pk_add_f32 v[12:13], v[12:13], v[152:153]
	v_lshlrev_b32_e32 v154, 16, v145
	v_and_b32_e32 v155, 0xffff0000, v145
	v_pk_add_f32 v[14:15], v[14:15], v[154:155]
	v_lshlrev_b32_e32 v152, 16, v146
	v_and_b32_e32 v153, 0xffff0000, v146
	v_pk_add_f32 v[8:9], v[8:9], v[152:153]
	v_lshlrev_b32_e32 v154, 16, v147
	v_and_b32_e32 v155, 0xffff0000, v147
	v_pk_add_f32 v[10:11], v[10:11], v[154:155]
	v_cvt_pk_bf16_f32 v144, v12, v13
	v_cvt_pk_bf16_f32 v145, v14, v15
	v_cvt_pk_bf16_f32 v146, v8, v9
	v_cvt_pk_bf16_f32 v147, v10, v11
	global_store_dwordx4 v[182:183], v[144:147], off
	v_pk_mul_f32 v[12:13], v[12:13], v[12:13]
	v_pk_mul_f32 v[14:15], v[14:15], v[14:15]
	v_pk_mul_f32 v[8:9], v[8:9], v[8:9]
	v_pk_mul_f32 v[10:11], v[10:11], v[10:11]
	v_add_f32_e32 v10, v10, v11
	v_add_f32_e32 v8, v8, v9
	v_add_f32_e32 v14, v14, v15
	v_add_f32_e32 v12, v12, v13
	v_add_f32_e32 v8, v8, v10
	v_add_f32_e32 v12, v12, v14
	v_add_f32_e32 v12, v12, v8
	s_waitcnt vmcnt(15)
	v_lshlrev_b32_e32 v152, 16, v148
	v_and_b32_e32 v153, 0xffff0000, v148
	v_pk_add_f32 v[4:5], v[4:5], v[152:153]
	v_lshlrev_b32_e32 v154, 16, v149
	v_and_b32_e32 v155, 0xffff0000, v149
	v_pk_add_f32 v[6:7], v[6:7], v[154:155]
	v_lshlrev_b32_e32 v152, 16, v150
	v_and_b32_e32 v153, 0xffff0000, v150
	v_pk_add_f32 v[0:1], v[0:1], v[152:153]
	v_lshlrev_b32_e32 v154, 16, v151
	v_and_b32_e32 v155, 0xffff0000, v151
	v_pk_add_f32 v[2:3], v[2:3], v[154:155]
	v_cvt_pk_bf16_f32 v148, v4, v5
	v_cvt_pk_bf16_f32 v149, v6, v7
	v_cvt_pk_bf16_f32 v150, v0, v1
	v_cvt_pk_bf16_f32 v151, v2, v3
	global_store_dwordx4 v[182:183], v[148:151], off offset:256
	v_pk_mul_f32 v[4:5], v[4:5], v[4:5]
	v_pk_mul_f32 v[6:7], v[6:7], v[6:7]
	v_pk_mul_f32 v[0:1], v[0:1], v[0:1]
	v_pk_mul_f32 v[2:3], v[2:3], v[2:3]
	v_add_f32_e32 v2, v2, v3
	v_add_f32_e32 v0, v0, v1
	v_add_f32_e32 v6, v6, v7
	v_add_f32_e32 v4, v4, v5
	v_add_f32_e32 v0, v0, v2
	v_add_f32_e32 v4, v4, v6
	v_add_f32_e32 v4, v4, v0
	v_add_f32_e32 v12, v12, v4
	ds_swizzle_b32 v13, v12 offset:swizzle(SWAP,16)
	s_waitcnt lgkmcnt(0)
	v_add_f32_e32 v128, v128, v129
	v_add_f32_e32 v112, v112, v113
	v_add_f32_e32 v96, v96, v97
	v_add_f32_e32 v80, v80, v81
	v_add_f32_e32 v60, v60, v61
	v_add_f32_e32 v44, v44, v45
	v_add_f32_e32 v28, v28, v29
	v_add_f32_e32 v12, v12, v13
	v_mov_b32_e32 v129, v128
	v_mov_b32_e32 v113, v112
	v_mov_b32_e32 v97, v96
	v_mov_b32_e32 v81, v80
	v_mov_b32_e32 v61, v60
	v_mov_b32_e32 v45, v44
	v_mov_b32_e32 v29, v28
	v_mov_b32_e32 v13, v12
	v_permlane32_swap_b32_e32 v128, v129
	v_permlane32_swap_b32_e32 v112, v113
	v_permlane32_swap_b32_e32 v96, v97
	v_permlane32_swap_b32_e32 v80, v81
	v_permlane32_swap_b32_e32 v60, v61
	v_permlane32_swap_b32_e32 v44, v45
	v_permlane32_swap_b32_e32 v28, v29
	v_permlane32_swap_b32_e32 v12, v13
	v_add_f32_e32 v128, v128, v129
	v_add_f32_e32 v112, v112, v113
	v_add_f32_e32 v96, v96, v97
	v_add_f32_e32 v80, v80, v81
	v_add_f32_e32 v60, v60, v61
	v_add_f32_e32 v44, v44, v45
	v_add_f32_e32 v28, v28, v29
	v_add_f32_e32 v12, v12, v13
	s_movk_i32 s6, 0x2000
	v_lshl_add_u64 v[152:153], v[66:67], 0, s[6:7]
	s_and_saveexec_b64 s[6:7], s[30:31]
	global_store_dword v[66:67], v128, off
	global_store_dword v[66:67], v112, off offset:1024
	global_store_dword v[66:67], v96, off offset:2048
	global_store_dword v[66:67], v80, off offset:3072
	global_store_dword v[152:153], v60, off
	global_store_dword v[152:153], v44, off offset:1024
	global_store_dword v[152:153], v28, off offset:2048
	global_store_dword v[152:153], v12, off offset:3072
	s_or_b64 exec, exec, s[6:7]
